# EVMIX: pool weight tile reload issues its 4 loads together (one round trip instead of four)
# speedup vs baseline: 1.0212x; 1.0026x over previous
; __device__ __forceinline__ void phase_evmix(const Params& p, unsigned char* lds, int e) {
;     ...
;             if (g != gl) {
;                 const bf16_t* Bt = poolT + (size_t)g * 128 * 128;
; #pragma unroll
;                 for (int k = 0; k < 4; ++k) { const int it = tid + k * NTHREADS; const int n = it >> 4, ch = it & 15; *(u32x4*)(Bl + n * 136 + ch * 8) = *(const u32x4*)(Bt + (size_t)n * 128 + ch * 8); }
;                 gl = g; }
.LBB0_915:
	s_lshl_b32 s4, s44, 4
	s_lshr_b32 s45, s44, 8
	s_add_i32 s45, s45, s44
	s_and_b32 s45, s45, 7
	s_and_b32 s42, s4, 0xffffff80
	s_mov_b64 s[36:37], -1
	s_cmp_gt_u32 s45, 3
	v_readfirstlane_b32 s43, v0
	s_waitcnt vmcnt(0)
	s_barrier
	s_cbranch_scc0 .LBB0_958
	s_add_i32 s36, s45, -4
	v_cmp_eq_u32_e32 vcc, s36, v212
	v_mov_b32_e32 v213, v212
	s_cbranch_vccnz .LBB0_918
	s_mov_b32 s37, s75
	s_lshl_b64 s[38:39], s[36:37], 15
	v_lshl_add_u64 v[2:3], v[150:151], 0, s[38:39]
	v_lshl_add_u64 v[60:61], v[2:3], 0, v[158:159]
	v_lshl_add_u64 v[64:65], v[2:3], 0, v[162:163]
	v_lshl_add_u64 v[68:69], v[2:3], 0, v[166:167]
	v_lshl_add_u64 v[72:73], v[2:3], 0, v[222:223]
	global_load_dwordx4 v[60:63], v[60:61], off
	global_load_dwordx4 v[64:67], v[64:65], off
	global_load_dwordx4 v[68:71], v[68:69], off
	global_load_dwordx4 v[72:75], v[72:73], off
	v_mov_b32_e32 v213, s36
	v_add_u32_e32 v1, v149, v157
	s_waitcnt vmcnt(3)
	ds_write_b128 v1, v[60:63]
	v_add_u32_e32 v1, v149, v161
	s_waitcnt vmcnt(2)
	ds_write_b128 v1, v[64:67]
	v_add_u32_e32 v1, v149, v165
	s_waitcnt vmcnt(1)
	ds_write_b128 v1, v[68:71]
	v_add_u32_e32 v1, v149, v169
	s_waitcnt vmcnt(0)
	ds_write_b128 v1, v[72:75]
